# sample rows of norm phases 5 and 13 processed by waves 1/5 inside the preceding grid barrier's wait (after arrival), phase proper skips them
# speedup vs baseline: 1.0096x; 1.0018x over previous
.LBB0_490:
	s_or_b64 exec, exec, s[0:1]
	v_readfirstlane_b32 s99, v145
	s_nop 1
	s_and_b32 s99, s99, 3
	s_cmp_lg_u32 s99, 1
	s_mov_b32 s99, 0
	s_cbranch_scc1 .Ln5_ret
	v_writelane_b32 v255, s56, 59
	v_writelane_b32 v255, s57, 60
	s_mov_b32 s99, 1
	s_branch .Ln5_body
.Ln5_ret:
	s_waitcnt lgkmcnt(0)
	s_barrier
.LBB0_491:
	s_cmp_lt_i32 s84, 6
	s_cselect_b64 s[0:1], -1, 0
	s_and_b64 s[4:5], s[0:1], s[4:5]
	s_andn2_b64 vcc, exec, s[4:5]
	s_cbranch_vccnz .LBB0_503
.Ln5_body:
	v_lshlrev_b32_e32 v48, 4, v144
	s_waitcnt lgkmcnt(0)
	global_load_dwordx4 v[0:3], v48, s[56:57]
	global_load_dwordx4 v[4:7], v48, s[56:57] offset:1024
	global_load_dwordx4 v[8:11], v48, s[56:57] offset:2048
	global_load_dwordx4 v[12:15], v48, s[56:57] offset:3072
	v_lshl_add_u32 v50, s2, 3, v145
	s_movk_i32 s0, 0x800
	v_lshlrev_b32_e32 v86, 2, v144
	v_mov_b32_e32 v53, 0
	s_lshl_b32 s30, s34, 3
	v_cmp_gt_i32_e32 vcc, s0, v50
	s_cmp_lg_u32 s99, 1
	s_cbranch_scc1 .Ln5_a
	s_mov_b64 vcc, 0
.Ln5_a:
	s_and_saveexec_b64 s[36:37], vcc
	s_cbranch_execz .LBB0_499
	v_mbcnt_lo_u32_b32 v17, -1, 0
	v_mbcnt_hi_u32_b32 v17, -1, v17
	v_and_b32_e32 v18, 64, v17
	v_add_u32_e32 v18, 64, v18
	v_xor_b32_e32 v19, 1, v17
	v_cmp_lt_i32_e32 vcc, v19, v18
	v_lshlrev_b32_e32 v16, 3, v144
	v_mov_b32_e32 v49, v53
	v_cndmask_b32_e32 v19, v17, v19, vcc
	v_lshlrev_b32_e32 v51, 2, v19
	v_xor_b32_e32 v19, 2, v17
	v_cmp_lt_i32_e32 vcc, v19, v18
	v_lshlrev_b32_e32 v52, 5, v144
	v_lshl_add_u64 v[54:55], s[24:25], 0, v[48:49]
	v_cndmask_b32_e32 v19, v17, v19, vcc
	v_lshlrev_b32_e32 v87, 2, v19
	v_xor_b32_e32 v19, 4, v17
	v_cmp_lt_i32_e32 vcc, v19, v18
	v_lshl_add_u64 v[56:57], s[56:57], 0, v[52:53]
	v_lshl_add_u64 v[58:59], s[94:95], 0, v[48:49]
	v_cndmask_b32_e32 v19, v17, v19, vcc
	v_lshlrev_b32_e32 v88, 2, v19
	v_xor_b32_e32 v19, 8, v17
	v_cmp_lt_i32_e32 vcc, v19, v18
	s_lshl_b32 s3, s34, 6
	s_mov_b64 s[48:49], 0
	v_cndmask_b32_e32 v19, v17, v19, vcc
	v_lshlrev_b32_e32 v89, 2, v19
	v_xor_b32_e32 v19, 16, v17
	v_cmp_lt_i32_e32 vcc, v19, v18
	s_mov_b64 s[50:51], 0x4000
	s_mov_b64 s[52:53], 0x3000
	v_cndmask_b32_e32 v19, v17, v19, vcc
	v_lshlrev_b32_e32 v90, 2, v19
	v_xor_b32_e32 v19, 32, v17
	v_cmp_lt_i32_e32 vcc, v19, v18
	v_or_b32_e32 v18, 0x200, v16
	v_lshlrev_b32_e32 v52, 2, v16
	v_cndmask_b32_e32 v17, v17, v19, vcc
	v_lshlrev_b32_e32 v91, 2, v17
	v_lshlrev_b32_e32 v17, 3, v145
	v_lshl_add_u32 v60, s2, 6, v17
	v_lshlrev_b32_e32 v62, 2, v18
	v_mov_b32_e32 v63, v53
	v_lshlrev_b32_e32 v64, 1, v16
	v_mov_b32_e32 v65, v53
	v_mov_b32_e32 v49, 0x358637bd
	s_mov_b32 s8, 0xf800000
	v_mov_b32_e32 v92, 0x260
	s_movk_i32 s9, 0x7ff
	v_mov_b32_e32 v93, v50
	s_branch .LBB0_495

.LBB0_499:
	s_or_b64 exec, exec, s[36:37]
	s_movk_i32 s0, 0x200
	v_and_b32_e32 v16, 3, v50
	v_lshrrev_b32_e32 v50, 2, v50
	v_cmp_eq_u32_e32 vcc, 1, v16
	s_cmp_eq_u32 s99, 1
	s_cbranch_scc1 .Ln5_b
	s_mov_b64 vcc, 0
.Ln5_b:
	s_and_saveexec_b64 s[36:37], vcc
	s_cbranch_execz .LBB0_502
	v_mbcnt_lo_u32_b32 v16, -1, 0
	v_mbcnt_hi_u32_b32 v16, -1, v16
	v_and_b32_e32 v18, 64, v16
	v_add_u32_e32 v18, 64, v18
	v_xor_b32_e32 v19, 1, v16
	v_cmp_lt_i32_e32 vcc, v19, v18
	v_ashrrev_i32_e32 v51, 31, v50
	v_lshlrev_b64 v[24:25], 12, v[50:51]
	v_cndmask_b32_e32 v19, v16, v19, vcc
	v_lshlrev_b32_e32 v40, 2, v19
	v_xor_b32_e32 v19, 2, v16
	v_cmp_lt_i32_e32 vcc, v19, v18
	s_mov_b64 s[12:13], s[84:85]
	v_lshl_add_u64 v[20:21], s[94:95], 0, v[24:25]
	v_cndmask_b32_e32 v19, v16, v19, vcc
	v_lshlrev_b32_e32 v41, 2, v19
	v_xor_b32_e32 v19, 4, v16
	v_cmp_lt_i32_e32 vcc, v19, v18
	s_mov_b64 s[14:15], s[86:87]
	v_readlane_b32 s80, v254, 11
	v_cndmask_b32_e32 v19, v16, v19, vcc
	v_lshlrev_b32_e32 v42, 2, v19
	v_xor_b32_e32 v19, 8, v16
	v_cmp_lt_i32_e32 vcc, v19, v18
	v_readlane_b32 s8, v254, 0
	v_readlane_b32 s84, v254, 15
	v_cndmask_b32_e32 v19, v16, v19, vcc
	v_lshlrev_b32_e32 v43, 2, v19
	v_xor_b32_e32 v19, 16, v16
	v_cmp_lt_i32_e32 vcc, v19, v18
	v_readlane_b32 s85, v254, 16
	v_readlane_b32 s86, v254, 17
	v_cndmask_b32_e32 v19, v16, v19, vcc
	v_lshlrev_b32_e32 v44, 2, v19
	v_xor_b32_e32 v19, 32, v16
	v_cmp_lt_i32_e32 vcc, v19, v18
	v_readlane_b32 s87, v254, 18
	v_readlane_b32 s90, v254, 21
	v_cndmask_b32_e32 v16, v16, v19, vcc
	v_readlane_b32 s91, v254, 22
	v_readlane_b32 s94, v254, 25
	v_readlane_b32 s95, v254, 26
	v_or_b32_e32 v28, 0x100, v86
	v_mov_b32_e32 v17, 0
	v_or_b32_e32 v30, 0x200, v86
	v_or_b32_e32 v32, 0x300, v86
	v_lshlrev_b32_e32 v45, 2, v16
	v_lshlrev_b32_e32 v16, 1, v86
	s_ashr_i32 s31, s30, 31
	v_readlane_b32 s9, v254, 1
	v_readlane_b32 s10, v254, 2
	v_readlane_b32 s11, v254, 3
	v_readlane_b32 s82, v254, 13
	v_readlane_b32 s83, v254, 14
	v_readlane_b32 s90, v254, 61
	s_mov_b64 s[86:87], s[14:15]
	v_readlane_b32 s94, v254, 59
	v_lshl_add_u64 v[18:19], s[24:25], 0, v[16:17]
	v_mov_b32_e32 v49, v17
	s_lshl_b64 s[48:49], s[30:31], 12
	v_lshl_add_u64 v[22:23], s[10:11], 0, v[24:25]
	v_readlane_b32 s91, v254, 62
	s_mov_b64 s[84:85], s[12:13]
	v_readlane_b32 s95, v254, 60
	v_lshl_add_u64 v[24:25], s[82:83], 0, v[24:25]
	s_mov_b64 s[38:39], 0
	s_mov_b32 s3, 0xe800000
	s_mov_b32 s6, 0xea00000
	s_mov_b32 s7, 0xec00000
	s_mov_b32 s8, 0xee00000
	s_mov_b32 s9, 0xf000000
	s_mov_b32 s10, 0xf200000
	s_mov_b32 s11, 0xf400000
	s_mov_b32 s12, 0xf600000
	s_mov_b32 s13, 0xf800000
	s_mov_b32 s14, 0xfa00000
	s_mov_b32 s15, 0x9000
	v_mov_b64_e32 v[26:27], s[96:97]
	s_brev_b32 s16, 32
	v_mov_b32_e32 v46, 0x358637bd
	v_mov_b32_e32 v47, 0x260
	s_mov_b64 s[50:51], 0x4000
	s_mov_b64 s[52:53], 0x3000
	v_lshlrev_b32_e32 v16, 2, v86
	v_lshlrev_b32_e32 v28, 2, v28
	v_mov_b32_e32 v29, v17
	v_lshlrev_b32_e32 v30, 2, v30
	v_mov_b32_e32 v31, v17
	v_lshlrev_b32_e32 v32, 2, v32
	v_mov_b32_e32 v33, v17
	s_movk_i32 s17, 0x1ff
	v_readlane_b32 s81, v254, 12
	v_readlane_b32 s88, v254, 19
	v_readlane_b32 s89, v254, 20
	v_readlane_b32 s92, v254, 23
	v_readlane_b32 s93, v254, 24

.LBB0_503:
	s_cmp_lg_u32 s99, 1
	s_cbranch_scc1 .Ln5_c
	s_mov_b64 exec, -1
	s_mov_b32 s99, 0
	v_readlane_b32 s56, v255, 59
	v_readlane_b32 s57, v255, 60
	s_mov_b64 s[4:5], -1
	s_branch .Ln5_ret

.LBB0_1385:
	s_or_b64 exec, exec, s[0:1]
	v_readfirstlane_b32 s99, v145
	s_nop 1
	s_and_b32 s99, s99, 3
	s_cmp_lg_u32 s99, 1
	s_mov_b32 s99, 0
	s_cbranch_scc1 .Ln13_ret
	v_writelane_b32 v255, s2, 59
	s_mov_b32 s99, 1
	s_branch .Ln13_body
.Ln13_ret:
	s_waitcnt lgkmcnt(0)
	s_barrier
.LBB0_1386:
	s_cmp_lt_i32 s84, 14
	s_cselect_b64 s[0:1], -1, 0
	s_and_b64 s[0:1], s[0:1], s[4:5]
	s_andn2_b64 vcc, exec, s[0:1]
	s_cbranch_vccnz .LBB0_1397
.Ln13_body:
	v_readlane_b32 s4, v254, 0
	v_lshlrev_b32_e32 v48, 4, v144
	v_readlane_b32 s5, v254, 1
	s_nop 4
	global_load_dwordx4 v[0:3], v48, s[4:5]
	global_load_dwordx4 v[4:7], v48, s[4:5] offset:1024
	global_load_dwordx4 v[8:11], v48, s[4:5] offset:2048
	global_load_dwordx4 v[12:15], v48, s[4:5] offset:3072
	v_lshl_add_u32 v50, s2, 3, v145
	s_movk_i32 s0, 0x800
	s_lshl_b32 s2, s34, 3
	v_cmp_gt_i32_e32 vcc, s0, v50
	v_ashrrev_i32_e32 v51, 31, v50
	v_mbcnt_lo_u32_b32 v49, -1, 0
	v_readlane_b32 s6, v254, 2
	v_readlane_b32 s7, v254, 3
	s_cmp_lg_u32 s99, 1
	s_cbranch_scc1 .Ln13_a
	s_mov_b64 vcc, 0
.Ln13_a:
	s_and_saveexec_b64 s[4:5], vcc
	s_cbranch_execz .LBB0_1394
	v_readlane_b32 s8, v254, 0
	v_lshlrev_b32_e32 v52, 5, v144
	v_readlane_b32 s9, v254, 1
	s_nop 4
	global_load_dwordx4 v[16:19], v52, s[8:9] offset:16
	global_load_dwordx4 v[20:23], v52, s[8:9]
	global_load_dwordx4 v[24:27], v52, s[8:9] offset:2064
	global_load_dwordx4 v[28:31], v52, s[8:9] offset:2048
	v_mbcnt_hi_u32_b32 v33, -1, v49
	v_and_b32_e32 v34, 64, v33
	v_add_u32_e32 v34, 64, v34
	v_xor_b32_e32 v35, 1, v33
	v_cmp_lt_i32_e32 vcc, v35, v34
	v_readlane_b32 s10, v254, 2
	v_readlane_b32 s11, v254, 3
	v_cndmask_b32_e32 v35, v33, v35, vcc
	v_lshlrev_b32_e32 v62, 2, v35
	v_xor_b32_e32 v35, 2, v33
	v_cmp_lt_i32_e32 vcc, v35, v34
	v_lshlrev_b32_e32 v32, 3, v144
	v_mov_b32_e32 v53, 0
	v_cndmask_b32_e32 v35, v33, v35, vcc
	v_lshlrev_b32_e32 v63, 2, v35
	v_xor_b32_e32 v35, 4, v33
	v_cmp_lt_i32_e32 vcc, v35, v34
	s_ashr_i32 s3, s2, 31
	v_lshl_add_u64 v[54:55], s[10:11], 0, v[52:53]
	v_cndmask_b32_e32 v35, v33, v35, vcc
	v_lshlrev_b32_e32 v64, 2, v35
	v_xor_b32_e32 v35, 8, v33
	v_cmp_lt_i32_e32 vcc, v35, v34
	s_lshl_b64 s[6:7], s[2:3], 14
	s_mov_b64 s[8:9], 0
	v_cndmask_b32_e32 v35, v33, v35, vcc
	v_lshlrev_b32_e32 v65, 2, v35
	v_xor_b32_e32 v35, 16, v33
	v_cmp_lt_i32_e32 vcc, v35, v34
	v_lshlrev_b32_e32 v52, 1, v32
	v_mov_b32_e32 v68, 0x358637bd
	v_cndmask_b32_e32 v35, v33, v35, vcc
	v_lshlrev_b32_e32 v66, 2, v35
	v_xor_b32_e32 v35, 32, v33
	v_cmp_lt_i32_e32 vcc, v35, v34
	s_mov_b32 s3, 0xf800000
	v_mov_b32_e32 v69, 0x260
	v_cndmask_b32_e32 v33, v33, v35, vcc
	v_lshlrev_b64 v[34:35], 14, v[50:51]
	v_lshl_or_b32 v34, v144, 4, v34
	v_lshlrev_b32_e32 v67, 2, v33
	v_lshl_add_u64 v[56:57], s[94:95], 0, v[34:35]
	s_movk_i32 s16, 0x7ff
	v_mov_b32_e32 v58, v50
	s_branch .LBB0_1390

.LBB0_1394:
	s_or_b64 exec, exec, s[4:5]
	s_movk_i32 s0, 0x200
	v_and_b32_e32 v16, 3, v50
	v_lshrrev_b32_e32 v50, 2, v50
	v_cmp_eq_u32_e32 vcc, 1, v16
	s_cmp_eq_u32 s99, 1
	s_cbranch_scc1 .Ln13_b
	s_mov_b64 vcc, 0
.Ln13_b:
	s_and_saveexec_b64 s[0:1], vcc
	s_cbranch_execz .LBB0_1397
	s_waitcnt vmcnt(0)
	v_mbcnt_hi_u32_b32 v16, -1, v49
	v_and_b32_e32 v17, 64, v16
	v_add_u32_e32 v17, 64, v17
	v_xor_b32_e32 v18, 1, v16
	v_cmp_lt_i32_e32 vcc, v18, v17
	v_readlane_b32 s8, v254, 0
	s_ashr_i32 s3, s2, 31
	v_cndmask_b32_e32 v18, v16, v18, vcc
	v_lshlrev_b32_e32 v24, 2, v18
	v_xor_b32_e32 v18, 2, v16
	v_cmp_lt_i32_e32 vcc, v18, v17
	v_readlane_b32 s9, v254, 1
	v_readlane_b32 s10, v254, 2
	v_cndmask_b32_e32 v18, v16, v18, vcc
	v_lshlrev_b32_e32 v25, 2, v18
	v_xor_b32_e32 v18, 4, v16
	v_cmp_lt_i32_e32 vcc, v18, v17
	v_readlane_b32 s11, v254, 3
	v_mov_b32_e32 v49, 0
	v_cndmask_b32_e32 v18, v16, v18, vcc
	v_lshlrev_b32_e32 v26, 2, v18
	v_xor_b32_e32 v18, 8, v16
	v_cmp_lt_i32_e32 vcc, v18, v17
	s_lshl_b64 s[4:5], s[2:3], 12
	s_mov_b64 s[6:7], 0
	v_cndmask_b32_e32 v18, v16, v18, vcc
	v_lshlrev_b32_e32 v27, 2, v18
	v_xor_b32_e32 v18, 16, v16
	v_cmp_lt_i32_e32 vcc, v18, v17
	s_mov_b32 s3, 0xe800000
	s_mov_b32 s8, 0xea00000
	v_cndmask_b32_e32 v18, v16, v18, vcc
	v_lshlrev_b32_e32 v28, 2, v18
	v_xor_b32_e32 v18, 32, v16
	v_cmp_lt_i32_e32 vcc, v18, v17
	s_mov_b32 s9, 0xec00000
	s_mov_b32 s12, 0xf200000
	v_cndmask_b32_e32 v16, v16, v18, vcc
	v_add_u32_e32 v18, 0x4000, v50
	v_ashrrev_i32_e32 v19, 31, v18
	v_lshlrev_b32_e32 v29, 2, v16
	v_lshlrev_b64 v[16:17], 12, v[50:51]
	v_lshlrev_b64 v[18:19], 12, v[18:19]
	v_lshl_add_u64 v[16:17], s[94:95], 0, v[16:17]
	v_lshl_add_u64 v[18:19], s[10:11], 0, v[18:19]
	s_mov_b32 s10, 0xee00000
	s_mov_b32 s11, 0xf000000
	s_mov_b32 s13, 0xf400000
	s_mov_b32 s14, 0xf600000
	s_mov_b32 s15, 0xf800000
	s_mov_b32 s16, 0xfa00000
	v_mov_b32_e32 v30, 0x358637bd
	v_mov_b32_e32 v31, 0x260
	s_movk_i32 s17, 0x1ff

.LBB0_1397:
	s_cmp_lg_u32 s99, 1
	s_cbranch_scc1 .Ln13_c
	s_mov_b64 exec, -1
	v_mbcnt_lo_u32_b32 v144, -1, 0
	v_mbcnt_hi_u32_b32 v144, -1, v144
	v_readlane_b32 s99, v255, 63
	s_nop 1
	s_lshr_b32 s99, s99, 6
	s_nop 0
	v_mov_b32_e32 v145, s99
	s_mov_b32 s99, 0
	v_readlane_b32 s2, v255, 59
	s_mov_b64 s[4:5], -1
	s_branch .Ln13_ret
